# P1 main K-loop back-edge rotation: increments + next-iteration pointer selects moved into the last MFMA segment
# baseline (speedup 1.0000x reference)
.Lp1rot_head:
	ds_read_b128 v[146:149], v150
	ds_read_b128 v[156:159], v150 offset:1024
	ds_read_b128 v[160:163], v150 offset:2048
	ds_read_b128 v[174:177], v150 offset:3072
	v_add_u32_e32 v150, s64, v153
	ds_read_b128 v[178:181], v150
	ds_read_b128 v[182:185], v150 offset:1024
	ds_read_b128 v[186:189], v150 offset:2048
	ds_read_b128 v[190:193], v150 offset:3072
	s_add_i32 m0, s9, 0xc000
	ds_read_b128 v[194:197], v155
	ds_read_b128 v[198:201], v155 offset:1024
	ds_read_b128 v[202:205], v155 offset:2048
	ds_read_b128 v[206:209], v155 offset:3072
	ds_read_b128 v[218:221], v155 offset:4096
	ds_read_b128 v[222:225], v155 offset:5120
	ds_read_b128 v[226:229], v155 offset:6144
	ds_read_b128 v[230:233], v155 offset:7168
	global_load_lds_dwordx4 v144, s[0:1]
	s_add_i32 m0, s9, 0xe000
	s_nop 0
	global_load_lds_dwordx4 v142, s[0:1]
	s_waitcnt vmcnt(8)
	s_waitcnt lgkmcnt(0)
	s_barrier
	s_setprio 1
	s_waitcnt lgkmcnt(0)
	v_mfma_f32_16x16x32_bf16 v[70:73], v[146:149], v[194:197], v[70:73]
	v_mfma_f32_16x16x32_bf16 v[66:69], v[160:163], v[194:197], v[66:69]
	v_mfma_f32_16x16x32_bf16 v[62:65], v[146:149], v[202:205], v[62:65]
	v_mfma_f32_16x16x32_bf16 v[58:61], v[160:163], v[202:205], v[58:61]
	v_mfma_f32_16x16x32_bf16 v[50:53], v[146:149], v[218:221], v[50:53]
	v_mfma_f32_16x16x32_bf16 v[46:49], v[160:163], v[218:221], v[46:49]
	v_mfma_f32_16x16x32_bf16 v[42:45], v[146:149], v[226:229], v[42:45]
	v_mfma_f32_16x16x32_bf16 v[38:41], v[160:163], v[226:229], v[38:41]
	v_mfma_f32_16x16x32_bf16 v[70:73], v[156:159], v[198:201], v[70:73]
	v_mfma_f32_16x16x32_bf16 v[66:69], v[174:177], v[198:201], v[66:69]
	v_mfma_f32_16x16x32_bf16 v[62:65], v[156:159], v[206:209], v[62:65]
	v_mfma_f32_16x16x32_bf16 v[58:61], v[174:177], v[206:209], v[58:61]
	v_mfma_f32_16x16x32_bf16 v[50:53], v[156:159], v[222:225], v[50:53]
	v_mfma_f32_16x16x32_bf16 v[46:49], v[174:177], v[222:225], v[46:49]
	v_mfma_f32_16x16x32_bf16 v[42:45], v[156:159], v[230:233], v[42:45]
	v_mfma_f32_16x16x32_bf16 v[38:41], v[174:177], v[230:233], v[38:41]
	s_setprio 0
	s_setprio 1
	v_mfma_f32_16x16x32_bf16 v[126:129], v[178:181], v[194:197], v[126:129]
	v_mfma_f32_16x16x32_bf16 v[122:125], v[186:189], v[194:197], v[122:125]
	v_mfma_f32_16x16x32_bf16 v[118:121], v[178:181], v[202:205], v[118:121]
	v_mfma_f32_16x16x32_bf16 v[114:117], v[186:189], v[202:205], v[114:117]
	v_mfma_f32_16x16x32_bf16 v[110:113], v[178:181], v[218:221], v[110:113]
	v_mfma_f32_16x16x32_bf16 v[106:109], v[186:189], v[218:221], v[106:109]
	v_mfma_f32_16x16x32_bf16 v[102:105], v[178:181], v[226:229], v[102:105]
	v_mfma_f32_16x16x32_bf16 v[98:101], v[186:189], v[226:229], v[98:101]
	v_mfma_f32_16x16x32_bf16 v[126:129], v[182:185], v[198:201], v[126:129]
	v_mfma_f32_16x16x32_bf16 v[122:125], v[190:193], v[198:201], v[122:125]
	v_mfma_f32_16x16x32_bf16 v[118:121], v[182:185], v[206:209], v[118:121]
	v_mfma_f32_16x16x32_bf16 v[114:117], v[190:193], v[206:209], v[114:117]
	v_mfma_f32_16x16x32_bf16 v[110:113], v[182:185], v[222:225], v[110:113]
	v_mfma_f32_16x16x32_bf16 v[106:109], v[190:193], v[222:225], v[106:109]
	v_mfma_f32_16x16x32_bf16 v[102:105], v[182:185], v[230:233], v[102:105]
	v_mfma_f32_16x16x32_bf16 v[98:101], v[190:193], v[230:233], v[98:101]
	s_setprio 0
	s_barrier
	s_add_i32 s30, s63, s8
	s_mov_b32 m0, s30
	ds_read_b128 v[194:197], v155 offset:16384
	ds_read_b128 v[198:201], v155 offset:17408
	ds_read_b128 v[202:205], v155 offset:18432
	ds_read_b128 v[206:209], v155 offset:19456
	ds_read_b128 v[218:221], v155 offset:20480
	ds_read_b128 v[222:225], v155 offset:21504
	ds_read_b128 v[226:229], v155 offset:22528
	ds_read_b128 v[230:233], v155 offset:23552
	global_load_lds_dwordx4 v134, s[48:49]
	s_add_i32 m0, s30, 0x2000
	s_add_u32 s30, s48, 0x80000
	s_mov_b64 s[82:83], s[48:49]
	s_addc_u32 s31, s49, 0
	s_add_i32 s63, s64, s8
	global_load_lds_dwordx4 v130, s[48:49]
	s_mov_b32 m0, s63
	s_nop 0
	global_load_lds_dwordx4 v134, s[30:31]
	s_add_i32 m0, s63, 0x2000
	s_nop 0
	global_load_lds_dwordx4 v130, s[30:31]
	s_mov_b32 m0, s9
	s_nop 0
	global_load_lds_dwordx4 v136, s[50:51]
	s_mov_b32 m0, s28
	s_nop 0
	global_load_lds_dwordx4 v132, s[50:51]
	s_waitcnt vmcnt(8)
	s_waitcnt lgkmcnt(0)
	s_barrier
	s_setprio 1
	s_waitcnt lgkmcnt(0)
	v_mfma_f32_16x16x32_bf16 v[30:33], v[146:149], v[194:197], v[30:33]
	v_mfma_f32_16x16x32_bf16 v[26:29], v[160:163], v[194:197], v[26:29]
	v_mfma_f32_16x16x32_bf16 v[22:25], v[146:149], v[202:205], v[22:25]
	v_mfma_f32_16x16x32_bf16 v[18:21], v[160:163], v[202:205], v[18:21]
	v_mfma_f32_16x16x32_bf16 v[14:17], v[146:149], v[218:221], v[14:17]
	v_mfma_f32_16x16x32_bf16 v[10:13], v[160:163], v[218:221], v[10:13]
	v_mfma_f32_16x16x32_bf16 v[6:9], v[146:149], v[226:229], v[6:9]
	v_mfma_f32_16x16x32_bf16 v[2:5], v[160:163], v[226:229], v[2:5]
	v_mfma_f32_16x16x32_bf16 v[30:33], v[156:159], v[198:201], v[30:33]
	v_mfma_f32_16x16x32_bf16 v[26:29], v[174:177], v[198:201], v[26:29]
	v_mfma_f32_16x16x32_bf16 v[22:25], v[156:159], v[206:209], v[22:25]
	v_mfma_f32_16x16x32_bf16 v[18:21], v[174:177], v[206:209], v[18:21]
	v_mfma_f32_16x16x32_bf16 v[14:17], v[156:159], v[222:225], v[14:17]
	v_mfma_f32_16x16x32_bf16 v[10:13], v[174:177], v[222:225], v[10:13]
	v_mfma_f32_16x16x32_bf16 v[6:9], v[156:159], v[230:233], v[6:9]
	v_mfma_f32_16x16x32_bf16 v[2:5], v[174:177], v[230:233], v[2:5]
	s_setprio 0
	s_setprio 1
	v_mfma_f32_16x16x32_bf16 v[94:97], v[178:181], v[194:197], v[94:97]
	v_mfma_f32_16x16x32_bf16 v[90:93], v[186:189], v[194:197], v[90:93]
	v_mfma_f32_16x16x32_bf16 v[86:89], v[178:181], v[202:205], v[86:89]
	v_mfma_f32_16x16x32_bf16 v[82:85], v[186:189], v[202:205], v[82:85]
	v_mfma_f32_16x16x32_bf16 v[78:81], v[178:181], v[218:221], v[78:81]
	v_mfma_f32_16x16x32_bf16 v[74:77], v[186:189], v[218:221], v[74:77]
	v_mfma_f32_16x16x32_bf16 v[54:57], v[178:181], v[226:229], v[54:57]
	v_mfma_f32_16x16x32_bf16 v[34:37], v[186:189], v[226:229], v[34:37]
	v_mfma_f32_16x16x32_bf16 v[94:97], v[182:185], v[198:201], v[94:97]
	v_mfma_f32_16x16x32_bf16 v[90:93], v[190:193], v[198:201], v[90:93]
	v_mfma_f32_16x16x32_bf16 v[86:89], v[182:185], v[206:209], v[86:89]
	v_mfma_f32_16x16x32_bf16 v[82:85], v[190:193], v[206:209], v[82:85]
	v_mfma_f32_16x16x32_bf16 v[78:81], v[182:185], v[222:225], v[78:81]
	v_mfma_f32_16x16x32_bf16 v[74:77], v[190:193], v[222:225], v[74:77]
	v_mfma_f32_16x16x32_bf16 v[54:57], v[182:185], v[230:233], v[54:57]
	v_mfma_f32_16x16x32_bf16 v[34:37], v[190:193], v[230:233], v[34:37]
	s_setprio 0
	s_barrier
	s_add_i32 s63, 0, 0x18000
	v_add_u32_e32 v172, s63, v153
	s_add_i32 s64, 0, 0x1c000
	ds_read_b128 v[146:149], v172
	ds_read_b128 v[156:159], v172 offset:1024
	ds_read_b128 v[160:163], v172 offset:2048
	ds_read_b128 v[174:177], v172 offset:3072
	v_add_u32_e32 v172, s64, v153
	ds_read_b128 v[178:181], v172
	ds_read_b128 v[182:185], v172 offset:1024
	ds_read_b128 v[186:189], v172 offset:2048
	ds_read_b128 v[190:193], v172 offset:3072
	s_add_u32 s30, s50, 0x80000
	s_addc_u32 s31, s51, 0
	s_mov_b32 m0, s29
	ds_read_b128 v[194:197], v155 offset:32768
	ds_read_b128 v[198:201], v155 offset:33792
	ds_read_b128 v[202:205], v155 offset:34816
	ds_read_b128 v[206:209], v155 offset:35840
	ds_read_b128 v[218:221], v155 offset:36864
	ds_read_b128 v[222:225], v155 offset:37888
	ds_read_b128 v[226:229], v155 offset:38912
	ds_read_b128 v[230:233], v155 offset:39936
	global_load_lds_dwordx4 v136, s[30:31]
	s_mov_b32 m0, s35
	s_nop 0
	global_load_lds_dwordx4 v132, s[30:31]
	s_waitcnt vmcnt(8)
	s_waitcnt lgkmcnt(0)
	s_barrier
	s_setprio 1
	s_waitcnt lgkmcnt(0)
	v_mfma_f32_16x16x32_bf16 v[70:73], v[146:149], v[194:197], v[70:73]
	v_mfma_f32_16x16x32_bf16 v[66:69], v[160:163], v[194:197], v[66:69]
	v_mfma_f32_16x16x32_bf16 v[62:65], v[146:149], v[202:205], v[62:65]
	v_mfma_f32_16x16x32_bf16 v[58:61], v[160:163], v[202:205], v[58:61]
	v_mfma_f32_16x16x32_bf16 v[50:53], v[146:149], v[218:221], v[50:53]
	v_mfma_f32_16x16x32_bf16 v[46:49], v[160:163], v[218:221], v[46:49]
	v_mfma_f32_16x16x32_bf16 v[42:45], v[146:149], v[226:229], v[42:45]
	v_mfma_f32_16x16x32_bf16 v[38:41], v[160:163], v[226:229], v[38:41]
	v_mfma_f32_16x16x32_bf16 v[70:73], v[156:159], v[198:201], v[70:73]
	v_mfma_f32_16x16x32_bf16 v[66:69], v[174:177], v[198:201], v[66:69]
	v_mfma_f32_16x16x32_bf16 v[62:65], v[156:159], v[206:209], v[62:65]
	v_mfma_f32_16x16x32_bf16 v[58:61], v[174:177], v[206:209], v[58:61]
	v_mfma_f32_16x16x32_bf16 v[50:53], v[156:159], v[222:225], v[50:53]
	v_mfma_f32_16x16x32_bf16 v[46:49], v[174:177], v[222:225], v[46:49]
	v_mfma_f32_16x16x32_bf16 v[42:45], v[156:159], v[230:233], v[42:45]
	v_mfma_f32_16x16x32_bf16 v[38:41], v[174:177], v[230:233], v[38:41]
	s_setprio 0
	s_setprio 1
	v_mfma_f32_16x16x32_bf16 v[126:129], v[178:181], v[194:197], v[126:129]
	v_mfma_f32_16x16x32_bf16 v[122:125], v[186:189], v[194:197], v[122:125]
	v_mfma_f32_16x16x32_bf16 v[118:121], v[178:181], v[202:205], v[118:121]
	v_mfma_f32_16x16x32_bf16 v[114:117], v[186:189], v[202:205], v[114:117]
	v_mfma_f32_16x16x32_bf16 v[110:113], v[178:181], v[218:221], v[110:113]
	v_mfma_f32_16x16x32_bf16 v[106:109], v[186:189], v[218:221], v[106:109]
	v_mfma_f32_16x16x32_bf16 v[102:105], v[178:181], v[226:229], v[102:105]
	v_mfma_f32_16x16x32_bf16 v[98:101], v[186:189], v[226:229], v[98:101]
	v_mfma_f32_16x16x32_bf16 v[126:129], v[182:185], v[198:201], v[126:129]
	v_mfma_f32_16x16x32_bf16 v[122:125], v[190:193], v[198:201], v[122:125]
	v_mfma_f32_16x16x32_bf16 v[118:121], v[182:185], v[206:209], v[118:121]
	v_mfma_f32_16x16x32_bf16 v[114:117], v[190:193], v[206:209], v[114:117]
	v_mfma_f32_16x16x32_bf16 v[110:113], v[182:185], v[222:225], v[110:113]
	v_mfma_f32_16x16x32_bf16 v[106:109], v[190:193], v[222:225], v[106:109]
	v_mfma_f32_16x16x32_bf16 v[102:105], v[182:185], v[230:233], v[102:105]
	v_mfma_f32_16x16x32_bf16 v[98:101], v[190:193], v[230:233], v[98:101]
	s_setprio 0
	s_barrier
	s_add_i32 s30, s63, s8
	s_add_i32 m0, s30, 0xffffff80
	ds_read_b128 v[194:197], v155 offset:49152
	ds_read_b128 v[198:201], v155 offset:50176
	ds_read_b128 v[202:205], v155 offset:51200
	ds_read_b128 v[206:209], v155 offset:52224
	ds_read_b128 v[218:221], v155 offset:53248
	ds_read_b128 v[222:225], v155 offset:54272
	ds_read_b128 v[226:229], v155 offset:55296
	ds_read_b128 v[230:233], v155 offset:56320
	global_load_lds_dwordx4 v134, s[48:49] offset:128
	s_add_i32 m0, s30, 0x1f80
	s_add_u32 s30, s48, 0x80080
	s_addc_u32 s31, s49, 0
	s_add_i32 s48, s64, s8
	global_load_lds_dwordx4 v130, s[82:83] offset:128
	s_mov_b32 m0, s48
	s_nop 0
	global_load_lds_dwordx4 v134, s[30:31]
	s_add_i32 m0, s48, 0x2000
	s_nop 0
	global_load_lds_dwordx4 v130, s[30:31]
	s_add_i32 m0, s52, 0xffffff80
	s_nop 0
	global_load_lds_dwordx4 v136, s[50:51] offset:128
	s_add_i32 m0, s53, 0xffffff80
	s_nop 0
	global_load_lds_dwordx4 v132, s[50:51] offset:128
	s_waitcnt vmcnt(8)
	s_waitcnt lgkmcnt(0)
	s_barrier
	s_setprio 1
	s_waitcnt lgkmcnt(0)
	v_mfma_f32_16x16x32_bf16 v[30:33], v[146:149], v[194:197], v[30:33]
	v_mfma_f32_16x16x32_bf16 v[26:29], v[160:163], v[194:197], v[26:29]
	v_mfma_f32_16x16x32_bf16 v[22:25], v[146:149], v[202:205], v[22:25]
	v_mfma_f32_16x16x32_bf16 v[18:21], v[160:163], v[202:205], v[18:21]
	v_mfma_f32_16x16x32_bf16 v[14:17], v[146:149], v[218:221], v[14:17]
	v_mfma_f32_16x16x32_bf16 v[10:13], v[160:163], v[218:221], v[10:13]
	v_mfma_f32_16x16x32_bf16 v[6:9], v[146:149], v[226:229], v[6:9]
	v_mfma_f32_16x16x32_bf16 v[2:5], v[160:163], v[226:229], v[2:5]
	v_mfma_f32_16x16x32_bf16 v[30:33], v[156:159], v[198:201], v[30:33]
	v_mfma_f32_16x16x32_bf16 v[26:29], v[174:177], v[198:201], v[26:29]
	v_mfma_f32_16x16x32_bf16 v[22:25], v[156:159], v[206:209], v[22:25]
	v_mfma_f32_16x16x32_bf16 v[18:21], v[174:177], v[206:209], v[18:21]
	v_mfma_f32_16x16x32_bf16 v[14:17], v[156:159], v[222:225], v[14:17]
	v_mfma_f32_16x16x32_bf16 v[10:13], v[174:177], v[222:225], v[10:13]
	v_mfma_f32_16x16x32_bf16 v[6:9], v[156:159], v[230:233], v[6:9]
	v_mfma_f32_16x16x32_bf16 v[2:5], v[174:177], v[230:233], v[2:5]
	s_setprio 0
	s_setprio 1
	s_add_i32 s62, s62, 2
	s_add_u32 s60, s60, 0x100
	s_addc_u32 s61, s61, 0
	s_add_u32 s0, s0, 0x100
	s_addc_u32 s1, s1, 0
	s_add_u32 s30, s0, 0xfff80080
	s_addc_u32 s31, s1, -1
	s_add_i32 s63, 0, 0x10000
	s_cmp_eq_u32 s62, 28
	s_cselect_b32 s51, s41, s31
	s_cselect_b32 s50, s47, s30
	v_add_u32_e32 v150, s63, v153
	s_cselect_b32 s49, s39, s61
	s_cselect_b32 s48, s55, s60
	s_add_i32 s64, 0, 0x14000
	s_cmp_gt_u32 s62, 29
	v_mfma_f32_16x16x32_bf16 v[94:97], v[178:181], v[194:197], v[94:97]
	v_mfma_f32_16x16x32_bf16 v[90:93], v[186:189], v[194:197], v[90:93]
	v_mfma_f32_16x16x32_bf16 v[86:89], v[178:181], v[202:205], v[86:89]
	v_mfma_f32_16x16x32_bf16 v[82:85], v[186:189], v[202:205], v[82:85]
	v_mfma_f32_16x16x32_bf16 v[78:81], v[178:181], v[218:221], v[78:81]
	v_mfma_f32_16x16x32_bf16 v[74:77], v[186:189], v[218:221], v[74:77]
	v_mfma_f32_16x16x32_bf16 v[54:57], v[178:181], v[226:229], v[54:57]
	v_mfma_f32_16x16x32_bf16 v[34:37], v[186:189], v[226:229], v[34:37]
	v_mfma_f32_16x16x32_bf16 v[94:97], v[182:185], v[198:201], v[94:97]
	v_mfma_f32_16x16x32_bf16 v[90:93], v[190:193], v[198:201], v[90:93]
	v_mfma_f32_16x16x32_bf16 v[86:89], v[182:185], v[206:209], v[86:89]
	v_mfma_f32_16x16x32_bf16 v[82:85], v[190:193], v[206:209], v[82:85]
	v_mfma_f32_16x16x32_bf16 v[78:81], v[182:185], v[222:225], v[78:81]
	v_mfma_f32_16x16x32_bf16 v[74:77], v[190:193], v[222:225], v[74:77]
	v_mfma_f32_16x16x32_bf16 v[54:57], v[182:185], v[230:233], v[54:57]
	v_mfma_f32_16x16x32_bf16 v[34:37], v[190:193], v[230:233], v[34:37]
	s_setprio 0
	s_barrier
	s_cbranch_scc0 .Lp1rot_head
	s_and_b64 vcc, exec, s[16:17]
	s_cbranch_vccz .LBB0_108
	s_barrier
